# MLA tile barrier moved behind step 17 so the two steps after it run on fragments fetched before the barrier and the next iteration's first LDS reads overlap them
# baseline (speedup 1.0000x reference)
; #define LAS __attribute__((address_space(3)))
; __device__ __forceinline__ float swap_max(float m) { auto rr = __builtin_amdgcn_permlane32_swap(__float_as_uint(m), __float_as_uint(m), false, false); return fmaxf(__uint_as_float(rr[0]), __uint_as_float(rr[1])); }
; #define MLA_PACK(P, b) (u32x4){cvt_pk_bf16(P[b], P[b + 1]), cvt_pk_bf16(P[b + 2], P[b + 3]), cvt_pk_bf16(P[b + 4], P[b + 5]), cvt_pk_bf16(P[b + 6], P[b + 7])}
; __device__ __forceinline__ void softmax_blk(f32x16& p0, f32x16& p1, f32x16& o0, f32x16& o1, float& mhat, float& lrun, u32x4 (&pf)[4], bool first) {
;     float r0 = max2_(p0[0], p0[1]), r1 = max2_(p1[0], p1[1]);
; #pragma unroll
;     for (int e = 2; e < 16; ++e) { r0 = max2_(r0, p0[e]); r1 = max2_(r1, p1[e]); }
;     const float rm = swap_max(max2_(r0, r1));
;     if (first || __any(rm - mhat > THR)) {
;         const float mn = first ? rm : fmaxf(rm, mhat); const float f = first ? 0.f : __builtin_amdgcn_exp2f(mhat - mn); mhat = mn; lrun *= f;
; #pragma unroll
;         for (int e = 0; e < 16; ++e) { o0[e] *= f; o1[e] *= f; }
;     }
;     float s0 = 0.f, s1 = 0.f;
; #pragma unroll
;     for (int e = 0; e < 16; ++e) { p0[e] = __builtin_amdgcn_exp2f(p0[e] - mhat); p1[e] = __builtin_amdgcn_exp2f(p1[e] - mhat); s0 += p0[e]; s1 += p1[e]; }
;     lrun += s0 + s1;
;     pf[0] = MLA_PACK(p0, 0); pf[1] = MLA_PACK(p0, 8); pf[2] = MLA_PACK(p1, 0); pf[3] = MLA_PACK(p1, 8);
; }
; __device__ __forceinline__ void attn_unit(const bf16_t* Qh, const bf16_t* Kh, const bf16_t* Vh, bf16_t* Oh  , int S, int qb, LAS unsigned char* lds, int tid) {
;     ...
;         {
;             f32x16 p0 = {}, p1 = {};
; #pragma unroll
;             for (int s = 0; s < 6; ++s) {
;                 const bf16x8 a0 = *(const LAS bf16x8*)(lds + cur + kfo + s * 32), a1 = *(const LAS bf16x8*)(lds + cur + kfo + 32 * KPITCH + s * 32);
;                 const bf16x8 q = *(const LAS bf16x8*)(ql + (6 + s) * 1024);
;                 p0 = __builtin_amdgcn_mfma_f32_32x32x16_bf16(a0, q, p0, 0, 0, 0); p1 = __builtin_amdgcn_mfma_f32_32x32x16_bf16(a1, q, p1, 0, 0, 0);
;             }
;             softmax_blk(p0, p1, ob0, ob1, mb, lb, pf, t == 0);
;             pv_blk(pf, ob0, ob1, lds + cur + vb);
;         }
;         *(LAS u32x4*)(lds + nxt + kd0) = ka; *(LAS u32x4*)(lds + (has1 ? nxt : 0u) + kd1) = kb; *(LAS u32x4*)(lds + nxt + vd) = va;
;         __syncthreads();
.Lmla_rescAp_back:
	v_exp_f32_e32 v64, v64
	v_exp_f32_e32 v65, v65
	v_exp_f32_e32 v66, v66
	v_exp_f32_e32 v67, v67
	v_exp_f32_e32 v68, v68
	v_exp_f32_e32 v69, v69
	v_exp_f32_e32 v70, v70
	v_exp_f32_e32 v71, v71
	v_add_f32_e32 v166, v64, v65
	v_add_f32_e32 v140, v140, v66
	v_add_f32_e32 v166, v166, v67
	v_cvt_pk_bf16_f32 v64, v64, v65
	v_cvt_pk_bf16_f32 v65, v66, v67
	v_exp_f32_e32 v72, v72
	v_exp_f32_e32 v73, v73
	v_exp_f32_e32 v74, v74
	v_exp_f32_e32 v75, v75
	v_add_f32_e32 v140, v140, v68
	v_add_f32_e32 v166, v166, v69
	v_add_f32_e32 v140, v140, v70
	v_add_f32_e32 v166, v166, v71
	v_cvt_pk_bf16_f32 v66, v68, v69
	v_cvt_pk_bf16_f32 v67, v70, v71
	v_exp_f32_e32 v76, v76
	s_waitcnt lgkmcnt(3)
	v_mfma_f32_32x32x16_bf16 v[96:111], v[128:131], v[162:165], v[96:111]
	v_mfma_f32_32x32x16_bf16 v[112:127], v[142:145], v[162:165], v[112:127]
	v_exp_f32_e32 v77, v77
	v_exp_f32_e32 v78, v78
	v_exp_f32_e32 v79, v79
	v_add_f32_e32 v140, v140, v72
	v_add_f32_e32 v166, v166, v73
	v_add_f32_e32 v140, v140, v74
	v_add_f32_e32 v166, v166, v75
	v_cvt_pk_bf16_f32 v68, v72, v73
	v_cvt_pk_bf16_f32 v69, v74, v75
	v_exp_f32_e32 v80, v80
	v_exp_f32_e32 v81, v81
	v_exp_f32_e32 v82, v82
	v_exp_f32_e32 v83, v83
	v_add_f32_e32 v140, v140, v76
	v_add_f32_e32 v166, v166, v77
	v_add_f32_e32 v140, v140, v78
	v_add_f32_e32 v166, v166, v79
	v_cvt_pk_bf16_f32 v70, v76, v77
	v_cvt_pk_bf16_f32 v71, v78, v79
	v_exp_f32_e32 v84, v84
	v_exp_f32_e32 v85, v85
	v_exp_f32_e32 v86, v86
	v_exp_f32_e32 v87, v87
	v_add_f32_e32 v140, v140, v80
	v_add_f32_e32 v166, v166, v81
	v_add_f32_e32 v140, v140, v82
	v_add_f32_e32 v166, v166, v83
	v_cvt_pk_bf16_f32 v72, v80, v81
	s_waitcnt lgkmcnt(0)
	v_mfma_f32_32x32x16_bf16 v[96:111], v[176:179], v[186:189], v[96:111]
	v_mfma_f32_32x32x16_bf16 v[112:127], v[180:183], v[186:189], v[112:127]
	v_cvt_pk_bf16_f32 v73, v82, v83
	v_exp_f32_e32 v88, v88
	v_exp_f32_e32 v89, v89
	v_exp_f32_e32 v90, v90
	v_exp_f32_e32 v91, v91
	v_add_f32_e32 v140, v140, v84
	v_add_f32_e32 v166, v166, v85
	v_add_f32_e32 v140, v140, v86
	v_add_f32_e32 v166, v166, v87
	v_cvt_pk_bf16_f32 v74, v84, v85
	v_cvt_pk_bf16_f32 v75, v86, v87
	v_exp_f32_e32 v92, v92
	v_exp_f32_e32 v93, v93
	v_exp_f32_e32 v94, v94
	v_exp_f32_e32 v95, v95
	v_add_f32_e32 v140, v140, v88
	v_add_f32_e32 v166, v166, v89
	v_add_f32_e32 v140, v140, v90
	v_add_f32_e32 v166, v166, v91
	v_cvt_pk_bf16_f32 v76, v88, v89
	v_cvt_pk_bf16_f32 v77, v90, v91
	v_add_f32_e32 v140, v140, v92
	v_add_f32_e32 v166, v166, v93
	v_add_f32_e32 v140, v140, v94
	v_add_f32_e32 v166, v166, v95
	v_cvt_pk_bf16_f32 v78, v92, v93
	v_cvt_pk_bf16_f32 v79, v94, v95
	v_add_f32_e32 v140, v140, v166
	s_nop 7
	s_nop 3
	v_max3_f32 v248, v96, v97, v98
	v_max3_f32 v249, v112, v113, v114
	v_max3_f32 v248, v248, v99, v100
	v_max3_f32 v249, v249, v115, v116
	v_max3_f32 v248, v248, v101, v102
	v_max3_f32 v249, v249, v117, v118
	v_max3_f32 v248, v248, v103, v104
	v_max3_f32 v249, v249, v119, v120
	v_max3_f32 v248, v248, v105, v106
	v_max3_f32 v249, v249, v121, v122
	v_max3_f32 v248, v248, v107, v108
	v_max3_f32 v249, v249, v123, v124
	v_max3_f32 v248, v248, v109, v110
	v_max3_f32 v249, v249, v125, v126
	v_max3_f32 v248, v248, v111, v127
	v_max_f32_e32 v248, v248, v249
	v_mov_b32_e32 v251, v248
	s_nop 1
	v_permlane32_swap_b32_e32 v248, v251
	v_max_f32_e32 v167, v248, v251
	v_sub_f32_e32 v96, v96, v167
	v_sub_f32_e32 v97, v97, v167
	v_sub_f32_e32 v98, v98, v167
	v_sub_f32_e32 v99, v99, v167
	v_sub_f32_e32 v100, v100, v167
	v_sub_f32_e32 v101, v101, v167
	v_sub_f32_e32 v102, v102, v167
	v_sub_f32_e32 v103, v103, v167
	v_sub_f32_e32 v104, v104, v167
	v_sub_f32_e32 v105, v105, v167
	v_sub_f32_e32 v106, v106, v167
	v_sub_f32_e32 v107, v107, v167
	v_sub_f32_e32 v108, v108, v167
	v_sub_f32_e32 v109, v109, v167
	v_sub_f32_e32 v110, v110, v167
	v_sub_f32_e32 v111, v111, v167
	v_sub_f32_e32 v112, v112, v167
	v_sub_f32_e32 v113, v113, v167
	v_sub_f32_e32 v114, v114, v167
	v_sub_f32_e32 v115, v115, v167
	v_sub_f32_e32 v116, v116, v167
	v_sub_f32_e32 v117, v117, v167
	v_sub_f32_e32 v118, v118, v167
	v_sub_f32_e32 v119, v119, v167
	v_sub_f32_e32 v120, v120, v167
	v_sub_f32_e32 v121, v121, v167
	v_sub_f32_e32 v122, v122, v167
	v_sub_f32_e32 v123, v123, v167
	v_sub_f32_e32 v124, v124, v167
	v_sub_f32_e32 v125, v125, v167
	v_sub_f32_e32 v126, v126, v167
	v_sub_f32_e32 v127, v127, v167
	v_sub_f32_e32 v190, 0, v167
	v_sub_f32_e32 v191, 0, v167
	v_sub_f32_e32 v192, 0, v167
	v_sub_f32_e32 v193, 0, v167
	v_sub_f32_e32 v194, 0, v167
	v_sub_f32_e32 v195, 0, v167
	v_sub_f32_e32 v196, 0, v167
	v_sub_f32_e32 v197, 0, v167
	v_sub_f32_e32 v198, 0, v167
	v_sub_f32_e32 v199, 0, v167
	v_sub_f32_e32 v200, 0, v167
	v_sub_f32_e32 v201, 0, v167
	v_sub_f32_e32 v202, 0, v167
	v_sub_f32_e32 v203, 0, v167
	v_sub_f32_e32 v204, 0, v167
	v_sub_f32_e32 v205, 0, v167
	s_waitcnt vmcnt(0)
	ds_write_b128 v150, v[218:221] offset:21504
	ds_write_b128 v159, v[222:225]
	s_waitcnt lgkmcnt(0)
	s_barrier
	ds_read_b64_tr_b16 v[128:129], v158 offset:13312
	ds_read_b64_tr_b16 v[130:131], v158 offset:13824
	ds_read_b64_tr_b16 v[142:143], v158 offset:17408
	ds_read_b64_tr_b16 v[144:145], v158 offset:17920
	ds_read_b64_tr_b16 v[176:177], v158 offset:14336
	ds_read_b64_tr_b16 v[178:179], v158 offset:14848
	ds_read_b64_tr_b16 v[180:181], v158 offset:18432
	ds_read_b64_tr_b16 v[182:183], v158 offset:18944
; #define LAS __attribute__((address_space(3)))
; __device__ __forceinline__ float max2_(float a, float b) { return __builtin_amdgcn_fmed3f(a, b, INFINITY); }
; __device__ __forceinline__ void softmax_blk(f32x16& p0, f32x16& p1, f32x16& o0, f32x16& o1, float& mhat, float& lrun, u32x4 (&pf)[4], bool first) {
;     float r0 = max2_(p0[0], p0[1]), r1 = max2_(p1[0], p1[1]);
; #pragma unroll
;     for (int e = 2; e < 16; ++e) { r0 = max2_(r0, p0[e]); r1 = max2_(r1, p1[e]); }
;     const float rm = swap_max(max2_(r0, r1));
;     if (first || __any(rm - mhat > THR)) {
;         const float mn = first ? rm : fmaxf(rm, mhat); const float f = first ? 0.f : __builtin_amdgcn_exp2f(mhat - mn); mhat = mn; lrun *= f;
; #pragma unroll
;         for (int e = 0; e < 16; ++e) { o0[e] *= f; o1[e] *= f; }
;     }
;     float s0 = 0.f, s1 = 0.f;
; #pragma unroll
;     for (int e = 0; e < 16; ++e) { p0[e] = __builtin_amdgcn_exp2f(p0[e] - mhat); p1[e] = __builtin_amdgcn_exp2f(p1[e] - mhat); s0 += p0[e]; s1 += p1[e]; }
;     lrun += s0 + s1;
;     pf[0] = MLA_PACK(p0, 0); pf[1] = MLA_PACK(p0, 8); pf[2] = MLA_PACK(p1, 0); pf[3] = MLA_PACK(p1, 8);
; }
; __device__ __forceinline__ void pv_blk(const u32x4 (&pf)[4], f32x16& o0, f32x16& o1, LAS const unsigned char* vbase) {
; #pragma unroll
;     for (int ks = 0; ks < 4; ++ks) {
;         const bf16x8 p = __builtin_bit_cast(bf16x8, pf[ks]);
;         { const s16x4 lo = vtr(vbase + ks * 1024), hh = vtr(vbase + ks * 1024 + 512); const bf16x8 vf = {lo[0], lo[1], lo[2], lo[3], hh[0], hh[1], hh[2], hh[3]};
;           o0 = __builtin_amdgcn_mfma_f32_32x32x16_bf16(vf, p, o0, 0, 0, 0); }
;         { const s16x4 lo = vtr(vbase + 4096 + ks * 1024), hh = vtr(vbase + 4096 + ks * 1024 + 512); const bf16x8 vf = {lo[0], lo[1], lo[2], lo[3], hh[0], hh[1], hh[2], hh[3]};
;           o1 = __builtin_amdgcn_mfma_f32_32x32x16_bf16(vf, p, o1, 0, 0, 0); }
;     }
; }
; __device__ __forceinline__ void attn_unit(const bf16_t* Qh, const bf16_t* Kh, const bf16_t* Vh, bf16_t* Oh  , int S, int qb, LAS unsigned char* lds, int tid) {
;     ...
;     for (int t = 0; t < NT; ++t) {
;         const unsigned cur = (unsigned)(t & 1) * BUF, nxt = BUF - cur;
;         const int tn = t + 1 < NT ? t + 1 : t;
;         ka = GLD(u32x4, Kg + (size_t)tn * 768 + kc0); kb = GLD(u32x4, Kg + (size_t)tn * 768 + kc1); va = GLD(u32x4, Vg + (size_t)tn * 512 + tid);
.Lmla_top:
	s_waitcnt lgkmcnt(4)
	v_mfma_f32_32x32x16_bf16 v[16:31], v[128:131], v[64:67], v[16:31]
	v_mfma_f32_32x32x16_bf16 v[0:15], v[142:145], v[64:67], v[0:15]
	ds_read_b64_tr_b16 v[128:129], v158 offset:15360
	ds_read_b64_tr_b16 v[130:131], v158 offset:15872
	ds_read_b64_tr_b16 v[142:143], v158 offset:19456
	ds_read_b64_tr_b16 v[144:145], v158 offset:19968
	global_load_dwordx4 v[218:221], v171, s[26:27]
	global_load_dwordx4 v[222:225], v184, s[26:27]
	global_load_dwordx4 v[226:229], v146, s[100:101]
	s_add_u32 s26, s26, 0x3000
	s_addc_u32 s27, s27, 0
	s_add_u32 s100, s100, 0x2000
	s_addc_u32 s101, s101, 0
	v_max3_f32 v248, v96, v97, v98
	v_max3_f32 v249, v112, v113, v114
	v_max3_f32 v248, v248, v99, v100
	v_max3_f32 v249, v249, v115, v116
	v_max3_f32 v248, v248, v101, v102
	v_max3_f32 v249, v249, v117, v118
	v_max3_f32 v248, v248, v103, v104
	v_max3_f32 v249, v249, v119, v120
	v_max3_f32 v248, v248, v105, v106
	v_max3_f32 v249, v249, v121, v122
	v_max3_f32 v248, v248, v107, v108
	s_waitcnt lgkmcnt(4)
	v_mfma_f32_32x32x16_bf16 v[16:31], v[176:179], v[68:71], v[16:31]
	v_mfma_f32_32x32x16_bf16 v[0:15], v[180:183], v[68:71], v[0:15]
	ds_read_b64_tr_b16 v[176:177], v158 offset:16384
	ds_read_b64_tr_b16 v[178:179], v158 offset:16896
	ds_read_b64_tr_b16 v[180:181], v158 offset:20480
	ds_read_b64_tr_b16 v[182:183], v158 offset:20992
	v_max3_f32 v249, v249, v123, v124
	v_max3_f32 v248, v248, v109, v110
	v_max3_f32 v249, v249, v125, v126
	v_max3_f32 v248, v248, v111, v127
	v_max_f32_e32 v248, v248, v249
	v_mov_b32_e32 v251, v248
	s_nop 1
	v_permlane32_swap_b32_e32 v248, v251
	v_max_f32_e32 v167, v248, v251
	v_cmp_lt_f32_e32 vcc, s72, v167
	s_waitcnt lgkmcnt(4)
	v_mfma_f32_32x32x16_bf16 v[16:31], v[128:131], v[72:75], v[16:31]
	v_mfma_f32_32x32x16_bf16 v[0:15], v[142:145], v[72:75], v[0:15]
	ds_read_b128 v[128:131], v155 offset:21504
	ds_read_b128 v[142:145], v155 offset:28160
	ds_read_b128 v[162:165], v135 offset:43008
	s_cbranch_vccnz .Lmla_rescBo

; #define LAS __attribute__((address_space(3)))
; __device__ __forceinline__ s16x4 vtr(LAS const unsigned char* p) { return __builtin_bit_cast(s16x4, __builtin_amdgcn_ds_read_tr16_b64_v4i16((LAS s16x4*)p)); }
; __device__ __forceinline__ void softmax_blk(f32x16& p0, f32x16& p1, f32x16& o0, f32x16& o1, float& mhat, float& lrun, u32x4 (&pf)[4], bool first) {
;     ...
;     for (int e = 0; e < 16; ++e) { p0[e] = __builtin_amdgcn_exp2f(p0[e] - mhat); p1[e] = __builtin_amdgcn_exp2f(p1[e] - mhat); s0 += p0[e]; s1 += p1[e]; }
;     lrun += s0 + s1;
;     pf[0] = MLA_PACK(p0, 0); pf[1] = MLA_PACK(p0, 8); pf[2] = MLA_PACK(p1, 0); pf[3] = MLA_PACK(p1, 8);
; }
; __device__ __forceinline__ void pv_blk(const u32x4 (&pf)[4], f32x16& o0, f32x16& o1, LAS const unsigned char* vbase) {
; #pragma unroll
;     for (int ks = 0; ks < 4; ++ks) {
;         const bf16x8 p = __builtin_bit_cast(bf16x8, pf[ks]);
;         { const s16x4 lo = vtr(vbase + ks * 1024), hh = vtr(vbase + ks * 1024 + 512); const bf16x8 vf = {lo[0], lo[1], lo[2], lo[3], hh[0], hh[1], hh[2], hh[3]};
;           o0 = __builtin_amdgcn_mfma_f32_32x32x16_bf16(vf, p, o0, 0, 0, 0); }
;         { const s16x4 lo = vtr(vbase + 4096 + ks * 1024), hh = vtr(vbase + 4096 + ks * 1024 + 512); const bf16x8 vf = {lo[0], lo[1], lo[2], lo[3], hh[0], hh[1], hh[2], hh[3]};
;           o1 = __builtin_amdgcn_mfma_f32_32x32x16_bf16(vf, p, o1, 0, 0, 0); }
;     }
; }
; __device__ __forceinline__ void attn_unit(const bf16_t* Qh, const bf16_t* Kh, const bf16_t* Vh, bf16_t* Oh  , int S, int qb, LAS unsigned char* lds, int tid) {
;     ...
;         {
;             f32x16 p0 = {}, p1 = {};
; #pragma unroll
;             for (int s = 0; s < 6; ++s) {
;                 const bf16x8 a0 = *(const LAS bf16x8*)(lds + cur + kfo + s * 32), a1 = *(const LAS bf16x8*)(lds + cur + kfo + 32 * KPITCH + s * 32);
;                 const bf16x8 q = *(const LAS bf16x8*)(ql + (6 + s) * 1024);
;                 p0 = __builtin_amdgcn_mfma_f32_32x32x16_bf16(a0, q, p0, 0, 0, 0); p1 = __builtin_amdgcn_mfma_f32_32x32x16_bf16(a1, q, p1, 0, 0, 0);
;             }
;             softmax_blk(p0, p1, ob0, ob1, mb, lb, pf, t == 0);
;             pv_blk(pf, ob0, ob1, lds + cur + vb);
;         }
;         *(LAS u32x4*)(lds + nxt + kd0) = ka; *(LAS u32x4*)(lds + (has1 ? nxt : 0u) + kd1) = kb; *(LAS u32x4*)(lds + nxt + vd) = va;
;         __syncthreads();
.Lmla_rescAo_back:
	v_exp_f32_e32 v64, v64
	v_exp_f32_e32 v65, v65
	v_exp_f32_e32 v66, v66
	v_exp_f32_e32 v67, v67
	v_exp_f32_e32 v68, v68
	v_exp_f32_e32 v69, v69
	v_exp_f32_e32 v70, v70
	v_exp_f32_e32 v71, v71
	v_add_f32_e32 v166, v64, v65
	s_waitcnt lgkmcnt(3)
	v_mfma_f32_32x32x16_bf16 v[48:63], v[176:179], v[108:111], v[48:63]
	v_mfma_f32_32x32x16_bf16 v[32:47], v[180:183], v[108:111], v[32:47]
	ds_read_b128 v[176:179], v155 offset:21536
	ds_read_b128 v[180:183], v155 offset:28192
	ds_read_b128 v[186:189], v135 offset:50176
	v_add_f32_e32 v140, v140, v66
	v_add_f32_e32 v166, v166, v67
	v_cvt_pk_bf16_f32 v64, v64, v65
	v_cvt_pk_bf16_f32 v65, v66, v67
	v_exp_f32_e32 v72, v72
	v_exp_f32_e32 v73, v73
	v_exp_f32_e32 v74, v74
	v_exp_f32_e32 v75, v75
	v_add_f32_e32 v140, v140, v68
	v_add_f32_e32 v166, v166, v69
	s_waitcnt lgkmcnt(3)
	v_mfma_f32_32x32x16_bf16 v[96:111], v[128:131], v[162:165], v[190:205]
	v_mfma_f32_32x32x16_bf16 v[112:127], v[142:145], v[162:165], v[190:205]
	ds_read_b128 v[128:131], v155 offset:21568
	ds_read_b128 v[142:145], v155 offset:28224
	ds_read_b128 v[162:165], v135 offset:51200
	v_add_f32_e32 v140, v140, v70
	v_add_f32_e32 v166, v166, v71
	v_cvt_pk_bf16_f32 v66, v68, v69
	v_cvt_pk_bf16_f32 v67, v70, v71
	v_exp_f32_e32 v76, v76
	v_exp_f32_e32 v77, v77
	v_exp_f32_e32 v78, v78
	v_exp_f32_e32 v79, v79
	v_add_f32_e32 v140, v140, v72
	v_add_f32_e32 v166, v166, v73
	s_waitcnt lgkmcnt(3)
	v_mfma_f32_32x32x16_bf16 v[96:111], v[176:179], v[186:189], v[96:111]
	v_mfma_f32_32x32x16_bf16 v[112:127], v[180:183], v[186:189], v[112:127]
	ds_read_b128 v[176:179], v155 offset:21600
	ds_read_b128 v[180:183], v155 offset:28256
	ds_read_b128 v[186:189], v135 offset:52224
	v_add_f32_e32 v140, v140, v74
	v_add_f32_e32 v166, v166, v75
	v_cvt_pk_bf16_f32 v68, v72, v73
	v_cvt_pk_bf16_f32 v69, v74, v75
	v_exp_f32_e32 v80, v80
	v_exp_f32_e32 v81, v81
	v_exp_f32_e32 v82, v82
	v_exp_f32_e32 v83, v83
	v_add_f32_e32 v140, v140, v76
	v_add_f32_e32 v166, v166, v77
	v_add_f32_e32 v140, v140, v78
	s_waitcnt lgkmcnt(3)
	v_mfma_f32_32x32x16_bf16 v[96:111], v[128:131], v[162:165], v[96:111]
	v_mfma_f32_32x32x16_bf16 v[112:127], v[142:145], v[162:165], v[112:127]
	ds_read_b128 v[128:131], v155 offset:21632
	ds_read_b128 v[142:145], v155 offset:28288
	ds_read_b128 v[162:165], v135 offset:53248
	v_add_f32_e32 v166, v166, v79
	v_cvt_pk_bf16_f32 v70, v76, v77
	v_cvt_pk_bf16_f32 v71, v78, v79
	v_exp_f32_e32 v84, v84
	v_exp_f32_e32 v85, v85
	v_exp_f32_e32 v86, v86
	v_exp_f32_e32 v87, v87
	v_add_f32_e32 v140, v140, v80
	v_add_f32_e32 v166, v166, v81
	v_add_f32_e32 v140, v140, v82
	s_waitcnt lgkmcnt(3)
	v_mfma_f32_32x32x16_bf16 v[96:111], v[176:179], v[186:189], v[96:111]
	v_mfma_f32_32x32x16_bf16 v[112:127], v[180:183], v[186:189], v[112:127]
	ds_read_b128 v[176:179], v155 offset:21664
	ds_read_b128 v[180:183], v155 offset:28320
	ds_read_b128 v[186:189], v135 offset:54272
	v_add_f32_e32 v166, v166, v83
	v_cvt_pk_bf16_f32 v72, v80, v81
	v_cvt_pk_bf16_f32 v73, v82, v83
	v_exp_f32_e32 v88, v88
	v_exp_f32_e32 v89, v89
	v_exp_f32_e32 v90, v90
	v_exp_f32_e32 v91, v91
	v_add_f32_e32 v140, v140, v84
	v_add_f32_e32 v166, v166, v85
	v_add_f32_e32 v140, v140, v86
	s_waitcnt vmcnt(0)
	ds_write_b128 v150, v[218:221]
	ds_write_b128 v156, v[222:225]
	ds_write_b128 v157, v[226:229] offset:34816
	s_waitcnt lgkmcnt(0)
	s_barrier
	v_mfma_f32_32x32x16_bf16 v[96:111], v[128:131], v[162:165], v[96:111]
	v_mfma_f32_32x32x16_bf16 v[112:127], v[142:145], v[162:165], v[112:127]
	ds_read_b64_tr_b16 v[128:129], v158 offset:34816
	ds_read_b64_tr_b16 v[130:131], v158 offset:35328
	ds_read_b64_tr_b16 v[142:143], v158 offset:38912
	ds_read_b64_tr_b16 v[144:145], v158 offset:39424
	v_add_f32_e32 v166, v166, v87
	v_cvt_pk_bf16_f32 v74, v84, v85
	v_cvt_pk_bf16_f32 v75, v86, v87
	v_exp_f32_e32 v92, v92
	v_exp_f32_e32 v93, v93
	v_exp_f32_e32 v94, v94
	v_exp_f32_e32 v95, v95
	v_add_f32_e32 v140, v140, v88
	v_add_f32_e32 v166, v166, v89
	v_add_f32_e32 v140, v140, v90
	v_mfma_f32_32x32x16_bf16 v[96:111], v[176:179], v[186:189], v[96:111]
	v_mfma_f32_32x32x16_bf16 v[112:127], v[180:183], v[186:189], v[112:127]
	ds_read_b64_tr_b16 v[176:177], v158 offset:35840
	ds_read_b64_tr_b16 v[178:179], v158 offset:36352
	ds_read_b64_tr_b16 v[180:181], v158 offset:39936
	ds_read_b64_tr_b16 v[182:183], v158 offset:40448
	v_add_f32_e32 v166, v166, v91
	v_cvt_pk_bf16_f32 v76, v88, v89
	v_cvt_pk_bf16_f32 v77, v90, v91
	v_add_f32_e32 v140, v140, v92
	v_add_f32_e32 v166, v166, v93
	v_add_f32_e32 v140, v140, v94
	v_add_f32_e32 v166, v166, v95
	v_cvt_pk_bf16_f32 v78, v92, v93
	v_cvt_pk_bf16_f32 v79, v94, v95
	v_add_f32_e32 v140, v140, v166
	s_add_i32 s1, s1, 1
	s_cmp_lg_u32 s1, s18
	s_cbranch_scc0 .Lmla_epi
	s_waitcnt lgkmcnt(4)
	v_mfma_f32_32x32x16_bf16 v[16:31], v[128:131], v[64:67], v[16:31]
	v_mfma_f32_32x32x16_bf16 v[0:15], v[142:145], v[64:67], v[0:15]
	ds_read_b64_tr_b16 v[128:129], v158 offset:36864
	ds_read_b64_tr_b16 v[130:131], v158 offset:37376
	ds_read_b64_tr_b16 v[142:143], v158 offset:40960
	ds_read_b64_tr_b16 v[144:145], v158 offset:41472
	global_load_dwordx4 v[218:221], v171, s[26:27]
	global_load_dwordx4 v[222:225], v184, s[26:27]
	global_load_dwordx4 v[226:229], v146, s[100:101]
	s_add_u32 s26, s26, 0x3000
	s_addc_u32 s27, s27, 0
	s_add_u32 s100, s100, 0x2000
	s_addc_u32 s101, s101, 0
	v_max3_f32 v248, v96, v97, v98
	v_max3_f32 v249, v112, v113, v114
	v_max3_f32 v248, v248, v99, v100
	v_max3_f32 v249, v249, v115, v116
	v_max3_f32 v248, v248, v101, v102
	v_max3_f32 v249, v249, v117, v118
	v_max3_f32 v248, v248, v103, v104
	v_max3_f32 v249, v249, v119, v120
	v_max3_f32 v248, v248, v105, v106
	v_max3_f32 v249, v249, v121, v122
	v_max3_f32 v248, v248, v107, v108
	s_waitcnt lgkmcnt(4)
	v_mfma_f32_32x32x16_bf16 v[16:31], v[176:179], v[68:71], v[16:31]
	v_mfma_f32_32x32x16_bf16 v[0:15], v[180:183], v[68:71], v[0:15]
	ds_read_b64_tr_b16 v[176:177], v158 offset:37888
	ds_read_b64_tr_b16 v[178:179], v158 offset:38400
	ds_read_b64_tr_b16 v[180:181], v158 offset:41984
	ds_read_b64_tr_b16 v[182:183], v158 offset:42496
	v_max3_f32 v249, v249, v123, v124
	v_max3_f32 v248, v248, v109, v110
	v_max3_f32 v249, v249, v125, v126
	v_max3_f32 v248, v248, v111, v127
	v_max_f32_e32 v248, v248, v249
	v_mov_b32_e32 v251, v248
	s_nop 1
	v_permlane32_swap_b32_e32 v248, v251
	v_max_f32_e32 v167, v248, v251
	v_cmp_lt_f32_e32 vcc, s72, v167
	s_waitcnt lgkmcnt(4)
	v_mfma_f32_32x32x16_bf16 v[16:31], v[128:131], v[72:75], v[16:31]
	v_mfma_f32_32x32x16_bf16 v[0:15], v[142:145], v[72:75], v[0:15]
	ds_read_b128 v[128:131], v155
	ds_read_b128 v[142:145], v155 offset:6656
	ds_read_b128 v[162:165], v135 offset:43008
	s_cbranch_vccnz .Lmla_rescBv

; #define LAS __attribute__((address_space(3)))
; __device__ __forceinline__ s16x4 vtr(LAS const unsigned char* p) { return __builtin_bit_cast(s16x4, __builtin_amdgcn_ds_read_tr16_b64_v4i16((LAS s16x4*)p)); }
; __device__ __forceinline__ void softmax_blk(f32x16& p0, f32x16& p1, f32x16& o0, f32x16& o1, float& mhat, float& lrun, u32x4 (&pf)[4], bool first) {
;     ...
;     for (int e = 0; e < 16; ++e) { p0[e] = __builtin_amdgcn_exp2f(p0[e] - mhat); p1[e] = __builtin_amdgcn_exp2f(p1[e] - mhat); s0 += p0[e]; s1 += p1[e]; }
;     lrun += s0 + s1;
;     pf[0] = MLA_PACK(p0, 0); pf[1] = MLA_PACK(p0, 8); pf[2] = MLA_PACK(p1, 0); pf[3] = MLA_PACK(p1, 8);
; }
; __device__ __forceinline__ void pv_blk(const u32x4 (&pf)[4], f32x16& o0, f32x16& o1, LAS const unsigned char* vbase) {
; #pragma unroll
;     for (int ks = 0; ks < 4; ++ks) {
;         const bf16x8 p = __builtin_bit_cast(bf16x8, pf[ks]);
;         { const s16x4 lo = vtr(vbase + ks * 1024), hh = vtr(vbase + ks * 1024 + 512); const bf16x8 vf = {lo[0], lo[1], lo[2], lo[3], hh[0], hh[1], hh[2], hh[3]};
;           o0 = __builtin_amdgcn_mfma_f32_32x32x16_bf16(vf, p, o0, 0, 0, 0); }
;         { const s16x4 lo = vtr(vbase + 4096 + ks * 1024), hh = vtr(vbase + 4096 + ks * 1024 + 512); const bf16x8 vf = {lo[0], lo[1], lo[2], lo[3], hh[0], hh[1], hh[2], hh[3]};
;           o1 = __builtin_amdgcn_mfma_f32_32x32x16_bf16(vf, p, o1, 0, 0, 0); }
;     }
; }
; __device__ __forceinline__ void attn_unit(const bf16_t* Qh, const bf16_t* Kh, const bf16_t* Vh, bf16_t* Oh  , int S, int qb, LAS unsigned char* lds, int tid) {
;     ...
;         {
;             f32x16 p0 = {}, p1 = {};
; #pragma unroll
;             for (int s = 0; s < 6; ++s) {
;                 const bf16x8 a0 = *(const LAS bf16x8*)(lds + cur + kfo + s * 32), a1 = *(const LAS bf16x8*)(lds + cur + kfo + 32 * KPITCH + s * 32);
;                 const bf16x8 q = *(const LAS bf16x8*)(ql + (6 + s) * 1024);
;                 p0 = __builtin_amdgcn_mfma_f32_32x32x16_bf16(a0, q, p0, 0, 0, 0); p1 = __builtin_amdgcn_mfma_f32_32x32x16_bf16(a1, q, p1, 0, 0, 0);
;             }
;             softmax_blk(p0, p1, ob0, ob1, mb, lb, pf, t == 0);
;             pv_blk(pf, ob0, ob1, lds + cur + vb);
;         }
;         *(LAS u32x4*)(lds + nxt + kd0) = ka; *(LAS u32x4*)(lds + (has1 ? nxt : 0u) + kd1) = kb; *(LAS u32x4*)(lds + nxt + vd) = va;
;         __syncthreads();
.Lmla_rescAe_back:
	v_exp_f32_e32 v64, v64
	v_exp_f32_e32 v65, v65
	v_exp_f32_e32 v66, v66
	v_exp_f32_e32 v67, v67
	v_exp_f32_e32 v68, v68
	v_exp_f32_e32 v69, v69
	v_exp_f32_e32 v70, v70
	v_exp_f32_e32 v71, v71
	v_add_f32_e32 v166, v64, v65
	s_waitcnt lgkmcnt(3)
	v_mfma_f32_32x32x16_bf16 v[48:63], v[176:179], v[108:111], v[48:63]
	v_mfma_f32_32x32x16_bf16 v[32:47], v[180:183], v[108:111], v[32:47]
	ds_read_b128 v[176:179], v155 offset:32
	ds_read_b128 v[180:183], v155 offset:6688
	ds_read_b128 v[186:189], v135 offset:50176
	v_add_f32_e32 v140, v140, v66
	v_add_f32_e32 v166, v166, v67
	v_cvt_pk_bf16_f32 v64, v64, v65
	v_cvt_pk_bf16_f32 v65, v66, v67
	v_exp_f32_e32 v72, v72
	v_exp_f32_e32 v73, v73
	v_exp_f32_e32 v74, v74
	v_exp_f32_e32 v75, v75
	v_add_f32_e32 v140, v140, v68
	v_add_f32_e32 v166, v166, v69
	s_waitcnt lgkmcnt(3)
	v_mfma_f32_32x32x16_bf16 v[96:111], v[128:131], v[162:165], v[190:205]
	v_mfma_f32_32x32x16_bf16 v[112:127], v[142:145], v[162:165], v[190:205]
	ds_read_b128 v[128:131], v155 offset:64
	ds_read_b128 v[142:145], v155 offset:6720
	ds_read_b128 v[162:165], v135 offset:51200
	v_add_f32_e32 v140, v140, v70
	v_add_f32_e32 v166, v166, v71
	v_cvt_pk_bf16_f32 v66, v68, v69
	v_cvt_pk_bf16_f32 v67, v70, v71
	v_exp_f32_e32 v76, v76
	v_exp_f32_e32 v77, v77
	v_exp_f32_e32 v78, v78
	v_exp_f32_e32 v79, v79
	v_add_f32_e32 v140, v140, v72
	v_add_f32_e32 v166, v166, v73
	s_waitcnt lgkmcnt(3)
	v_mfma_f32_32x32x16_bf16 v[96:111], v[176:179], v[186:189], v[96:111]
	v_mfma_f32_32x32x16_bf16 v[112:127], v[180:183], v[186:189], v[112:127]
	ds_read_b128 v[176:179], v155 offset:96
	ds_read_b128 v[180:183], v155 offset:6752
	ds_read_b128 v[186:189], v135 offset:52224
	v_add_f32_e32 v140, v140, v74
	v_add_f32_e32 v166, v166, v75
	v_cvt_pk_bf16_f32 v68, v72, v73
	v_cvt_pk_bf16_f32 v69, v74, v75
	v_exp_f32_e32 v80, v80
	v_exp_f32_e32 v81, v81
	v_exp_f32_e32 v82, v82
	v_exp_f32_e32 v83, v83
	v_add_f32_e32 v140, v140, v76
	v_add_f32_e32 v166, v166, v77
	v_add_f32_e32 v140, v140, v78
	s_waitcnt lgkmcnt(3)
	v_mfma_f32_32x32x16_bf16 v[96:111], v[128:131], v[162:165], v[96:111]
	v_mfma_f32_32x32x16_bf16 v[112:127], v[142:145], v[162:165], v[112:127]
	ds_read_b128 v[128:131], v155 offset:128
	ds_read_b128 v[142:145], v155 offset:6784
	ds_read_b128 v[162:165], v135 offset:53248
	v_add_f32_e32 v166, v166, v79
	v_cvt_pk_bf16_f32 v70, v76, v77
	v_cvt_pk_bf16_f32 v71, v78, v79
	v_exp_f32_e32 v84, v84
	v_exp_f32_e32 v85, v85
	v_exp_f32_e32 v86, v86
	v_exp_f32_e32 v87, v87
	v_add_f32_e32 v140, v140, v80
	v_add_f32_e32 v166, v166, v81
	v_add_f32_e32 v140, v140, v82
	s_waitcnt lgkmcnt(3)
	v_mfma_f32_32x32x16_bf16 v[96:111], v[176:179], v[186:189], v[96:111]
	v_mfma_f32_32x32x16_bf16 v[112:127], v[180:183], v[186:189], v[112:127]
	ds_read_b128 v[176:179], v155 offset:160
	ds_read_b128 v[180:183], v155 offset:6816
	ds_read_b128 v[186:189], v135 offset:54272
	v_add_f32_e32 v166, v166, v83
	v_cvt_pk_bf16_f32 v72, v80, v81
	v_cvt_pk_bf16_f32 v73, v82, v83
	v_exp_f32_e32 v88, v88
	v_exp_f32_e32 v89, v89
	v_exp_f32_e32 v90, v90
	v_exp_f32_e32 v91, v91
	v_add_f32_e32 v140, v140, v84
	v_add_f32_e32 v166, v166, v85
	v_add_f32_e32 v140, v140, v86
	s_waitcnt vmcnt(0)
	ds_write_b128 v150, v[218:221] offset:21504
	ds_write_b128 v159, v[222:225]
	ds_write_b128 v157, v[226:229] offset:13312
	s_waitcnt lgkmcnt(0)
	s_barrier
	v_mfma_f32_32x32x16_bf16 v[96:111], v[128:131], v[162:165], v[96:111]
	v_mfma_f32_32x32x16_bf16 v[112:127], v[142:145], v[162:165], v[112:127]
	ds_read_b64_tr_b16 v[128:129], v158 offset:13312
	ds_read_b64_tr_b16 v[130:131], v158 offset:13824
	ds_read_b64_tr_b16 v[142:143], v158 offset:17408
	ds_read_b64_tr_b16 v[144:145], v158 offset:17920
	v_add_f32_e32 v166, v166, v87
	v_cvt_pk_bf16_f32 v74, v84, v85
	v_cvt_pk_bf16_f32 v75, v86, v87
	v_exp_f32_e32 v92, v92
	v_exp_f32_e32 v93, v93
	v_exp_f32_e32 v94, v94
	v_exp_f32_e32 v95, v95
	v_add_f32_e32 v140, v140, v88
	v_add_f32_e32 v166, v166, v89
	v_add_f32_e32 v140, v140, v90
	v_mfma_f32_32x32x16_bf16 v[96:111], v[176:179], v[186:189], v[96:111]
	v_mfma_f32_32x32x16_bf16 v[112:127], v[180:183], v[186:189], v[112:127]
	ds_read_b64_tr_b16 v[176:177], v158 offset:14336
	ds_read_b64_tr_b16 v[178:179], v158 offset:14848
	ds_read_b64_tr_b16 v[180:181], v158 offset:18432
	ds_read_b64_tr_b16 v[182:183], v158 offset:18944
	v_add_f32_e32 v166, v166, v91
	v_cvt_pk_bf16_f32 v76, v88, v89
	v_cvt_pk_bf16_f32 v77, v90, v91
	v_add_f32_e32 v140, v140, v92
	v_add_f32_e32 v166, v166, v93
	v_add_f32_e32 v140, v140, v94
	v_add_f32_e32 v166, v166, v95
	v_cvt_pk_bf16_f32 v78, v92, v93
	v_cvt_pk_bf16_f32 v79, v94, v95
	v_add_f32_e32 v140, v140, v166
	s_add_i32 s1, s1, 1
	s_branch .Lmla_top
.Lmla_epi:
	s_waitcnt lgkmcnt(4)
	v_mfma_f32_32x32x16_bf16 v[16:31], v[128:131], v[64:67], v[16:31]
	v_mfma_f32_32x32x16_bf16 v[0:15], v[142:145], v[64:67], v[0:15]
	ds_read_b64_tr_b16 v[128:129], v158 offset:36864
	ds_read_b64_tr_b16 v[130:131], v158 offset:37376
	ds_read_b64_tr_b16 v[142:143], v158 offset:40960
	ds_read_b64_tr_b16 v[144:145], v158 offset:41472
	v_max3_f32 v248, v96, v97, v98
	v_max3_f32 v249, v112, v113, v114
	v_max3_f32 v248, v248, v99, v100
	v_max3_f32 v249, v249, v115, v116
	v_max3_f32 v248, v248, v101, v102
	v_max3_f32 v249, v249, v117, v118
	v_max3_f32 v248, v248, v103, v104
	v_max3_f32 v249, v249, v119, v120
	v_max3_f32 v248, v248, v105, v106
	v_max3_f32 v249, v249, v121, v122
	v_max3_f32 v248, v248, v107, v108
	v_max3_f32 v249, v249, v123, v124
	v_max3_f32 v248, v248, v109, v110
	v_max3_f32 v249, v249, v125, v126
	v_max3_f32 v248, v248, v111, v127
	v_max_f32_e32 v248, v248, v249
	v_mov_b32_e32 v251, v248
	s_nop 1
	v_permlane32_swap_b32_e32 v248, v251
	v_max_f32_e32 v167, v248, v251
	v_cmp_lt_f32_e32 vcc, s72, v167
	s_cbranch_vccnz .Lmla_rescBe
